# wkv scan phase: the new-state outputs (prompt final state and sample state, never re-read) stored non-temporal
# baseline (speedup 1.0000x reference)
; __device__ __forceinline__ void ph_wkv2(const Params& p, int jl, int lane, int wave) {
;     ...
;         const int it = job & 3, h = (job >> 2) & 15, seq = job >> 6, r0 = seq * TP;
;         const unsigned char* rec = p.ws + WS_REC + (size_t)((seq * WH + h) * WC_NCH) * REC_BYTES;
;     ...
;         static_assert(WC_NCH % 2 == 1, "chunk loop unrolled by two plus one");
;         WC_LOAD(RA, rec); WC_LOAD(RB, rec + REC_BYTES);
;         v2u ypk = (v2u){0u, 0u};
;         for (int c = 0; c + 1 < WC_NCH; c += 2) { WC_STEP(RA, RB, c); WC_STEP(RB, RA, c + 1); }
;         WC_STEP(RA, RB, WC_NCH - 1);
;         *(v2u*)(YW + (size_t)(r0 + WC_C * (WC_NCH - 1) + 4 * fq + (fr & 3)) * D + h * WN + 16 * it + (fr & 12)) = ypk;
;     ...
;         float* so = p.out + O_WKVP + ((((size_t)jl * BATCH + seq) * WH + h) * WN + 16 * it + fr) * WN + 4 * fq;
; #pragma unroll
;         for (int jt = 0; jt < 4; ++jt) *(f32x4*)(so + 16 * jt) = Sacc[jt];
.LBB0_130:
	s_waitcnt vmcnt(13)
	v_mov_b32_e32 v204, 0x1000
	s_mov_b64 s[14:15], exec
	s_mov_b64 exec, 1
	ds_write_b32 v1, v204
	s_mov_b64 exec, s[14:15]
	v_add_u32_e32 v54, s12, v182
	v_ashrrev_i32_e32 v55, 31, v54
	v_lshlrev_b64 v[54:55], 11, v[54:55]
	v_lshl_add_u64 v[54:55], s[34:35], 0, v[54:55]
	s_lshl_b32 s94, s13, 1
	v_lshl_add_u64 v[54:55], v[54:55], 0, s[94:95]
	s_lshl_b32 s0, s18, 1
	s_mov_b32 s1, s95
	v_lshl_add_u64 v[54:55], v[54:55], 0, s[0:1]
	v_mov_b32_e32 v171, v1
	v_lshl_add_u64 v[54:55], v[54:55], 0, v[170:171]
	global_store_dwordx2 v[54:55], v[30:31], off
	s_waitcnt vmcnt(2)
	v_mfma_f32_16x16x16_bf16 v[54:57], v[102:103], v[32:33], 0
	v_cvt_pk_bf16_f32 v63, v144, v145
	v_cvt_pk_bf16_f32 v62, v142, v143
	v_cvt_pk_bf16_f32 v65, v124, v125
	v_cvt_pk_bf16_f32 v64, v122, v123
	v_mfma_f32_16x16x16_bf16 v[58:61], v[104:105], v[32:33], 0
	s_nop 2
	v_add_f32_e64 v56, v56, 0
	v_add_f32_e64 v57, v57, 0
	v_pk_add_f32 v[54:55], v[54:55], 0 op_sel_hi:[1,0]
	v_cvt_pk_bf16_f32 v67, v120, v121
	v_cvt_pk_bf16_f32 v66, v118, v119
	v_mfma_f32_16x16x32_bf16 v[2:5], v[2:5], v[62:65], v[54:57]
	v_cvt_pk_bf16_f32 v69, v116, v117
	v_cvt_pk_bf16_f32 v68, v114, v115
	v_pk_add_f32 v[60:61], v[60:61], 0 op_sel_hi:[1,0]
	v_pk_add_f32 v[58:59], v[58:59], 0 op_sel_hi:[1,0]
	v_mfma_f32_16x16x32_bf16 v[2:5], v[10:13], v[66:69], v[2:5]
	s_nop 0
	v_mfma_f32_16x16x32_bf16 v[10:13], v[46:49], v[62:65], v[58:61]
	v_mfma_f32_16x16x32_bf16 v[10:13], v[42:45], v[66:69], v[10:13]
	s_nop 4
	v_cvt_pk_bf16_f32 v31, v4, v5
	v_cvt_pk_bf16_f32 v30, v2, v3
	s_nop 1
	v_mfma_f32_16x16x32_bf16 v[6:9], v[6:9], v[30:33], v[114:117]
	v_cndmask_b32_e64 v0, v10, v11, s[4:5]
	s_nop 1
	v_mov_b32_dpp v0, v0 quad_perm:[1,0,3,2] row_mask:0xf bank_mask:0xf bound_ctrl:1
	v_cndmask_b32_e64 v10, v0, v10, s[4:5]
	s_nop 2
	v_pk_mul_f32 v[6:7], v[18:19], v[6:7]
	v_cndmask_b32_e64 v18, v12, v13, s[4:5]
	v_cndmask_b32_e64 v0, v11, v0, s[4:5]
	v_mfma_f32_16x16x32_bf16 v[2:5], v[38:41], v[30:33], v[142:145]
	v_mov_b32_dpp v18, v18 quad_perm:[1,0,3,2] row_mask:0xf bank_mask:0xf bound_ctrl:1
	v_cndmask_b32_e64 v11, v18, v12, s[4:5]
	v_cndmask_b32_e64 v12, v13, v18, s[4:5]
	v_cndmask_b32_e64 v13, v10, v11, s[6:7]
	v_cndmask_b32_e64 v18, v0, v12, s[6:7]
	v_mfma_f32_16x16x32_bf16 v[26:29], v[26:29], v[30:33], v[122:125]
	v_mov_b32_dpp v13, v13 quad_perm:[2,3,0,1] row_mask:0xf bank_mask:0xf bound_ctrl:1
	v_mov_b32_dpp v18, v18 quad_perm:[2,3,0,1] row_mask:0xf bank_mask:0xf bound_ctrl:1
	v_cndmask_b32_e64 v11, v11, v13, s[6:7]
	v_cndmask_b32_e64 v12, v12, v18, s[6:7]
	v_cvt_pk_bf16_f32 v11, v11, v12
	v_add_u32_e32 v12, s12, v183
	v_cndmask_b32_e64 v10, v13, v10, s[6:7]
	v_ashrrev_i32_e32 v13, 31, v12
	v_lshlrev_b64 v[12:13], 11, v[12:13]
	v_lshl_add_u64 v[12:13], s[34:35], 0, v[12:13]
	v_lshl_add_u64 v[12:13], v[12:13], 0, s[94:95]
	v_lshl_add_u64 v[12:13], v[12:13], 0, s[0:1]
	s_ashr_i32 s1, s11, 31
	s_add_u32 s0, s11, s3
	v_cndmask_b32_e64 v0, v18, v0, s[6:7]
	s_addc_u32 s1, s1, 0
	v_cvt_pk_bf16_f32 v10, v10, v0
	v_lshl_add_u64 v[12:13], v[12:13], 0, v[170:171]
	s_lshl_b64 s[0:1], s[0:1], 10
	v_mfma_f32_16x16x32_bf16 v[14:17], v[14:17], v[30:33], v[118:121]
	global_store_dwordx2 v[12:13], v[10:11], off
	v_or_b32_e32 v0, s0, v150
	v_mov_b32_e32 v10, s18
	v_or3_b32 v11, s1, 0, 0
	v_or3_b32 v10, v0, s13, v10
	v_lshlrev_b64 v[10:11], 8, v[10:11]
	s_add_i32 s2, s2, s9
	s_sub_i32 s10, s10, s9
	v_pk_mul_f32 v[4:5], v[52:53], v[4:5]
	v_pk_mul_f32 v[2:3], v[50:51], v[2:3]
	v_lshl_add_u64 v[10:11], v[168:169], 0, v[10:11]
	s_cmpk_gt_i32 s2, 0x1ff
	v_pk_mul_f32 v[28:29], v[36:37], v[28:29]
	v_pk_mul_f32 v[26:27], v[34:35], v[26:27]
	v_pk_mul_f32 v[16:17], v[24:25], v[16:17]
	v_pk_mul_f32 v[14:15], v[22:23], v[14:15]
	v_pk_mul_f32 v[8:9], v[20:21], v[8:9]
	global_store_dwordx4 v[10:11], v[2:5], off nt
	global_store_dwordx4 v[10:11], v[26:29], off offset:64 nt
	global_store_dwordx4 v[10:11], v[14:17], off offset:128 nt
	global_store_dwordx4 v[10:11], v[6:9], off offset:192 nt
	s_cbranch_scc1 .LBB0_136

; __device__ __forceinline__ f32x4 wk_unit_neg(const f32x4 kraw, const f32x4 kkp) {
;     const f32x4 kk = kraw * kkp;
;     const float ss = row16_sum((kk.x * kk.x + kk.y * kk.y) + (kk.z * kk.z + kk.w * kk.w));
;     return kk * (-rsqrtf(fmaxf(ss, 1e-12f)));
; }
; __device__ __forceinline__ void ph_wkv2(const Params& p, int jl, int lane, int wave) {
;     ...
;                 const int rg = it & 15, h = (it >> 4) & 15, s = it >> 8, row = MP + s, i = 4 * rg + ri;
;                 const int ch = h * WN + 4 * cg;
;                 WkPar P; P.w0 = *(const f32x4*)(p.in[I_W0] + (size_t)jl * D + ch); P.a0 = *(const f32x4*)(p.in[I_A0] + (size_t)jl * D + ch); P.kkp = *(const f32x4*)(p.in[I_KK] + (size_t)jl * D + ch);
;                 P.kap = *(const f32x4*)(p.in[I_KA] + (size_t)jl * D + ch); P.v0 = *(const f32x4*)(p.in[I_V0] + ch);
;                 const size_t vo = (size_t)row * D + ch;
;     ...
;                 const f32x4 kraw = W2_UP4(qk[q]), vraw = W2_UP4(qv[q]), r4 = W2_UP4(qr[q]), lw2 = W2_UP4(qlw[q]), la2 = W2_UP4(qla[q]), vf = W2_UP4(qvf[q]), lv2 = W2_UP4(qlv[q]);
;     ...
;                 f32x4 w4, ka, k4, vp, nk; wk_prep(P, kraw, vraw, lw2, la2, vf, lv2, vres, w4, ka, k4, vp, nk);
;                 const int srcl = (lane & 48) | rg;
;                 const float v0_ = shfl_l(vp.x, srcl), v1_ = shfl_l(vp.y, srcl), v2_ = shfl_l(vp.z, srcl), v3_ = shfl_l(vp.w, srcl);
;                 const float vi = ri == 0 ? v0_ : (ri == 1 ? v1_ : (ri == 2 ? v2_ : v3_));
;                 const size_t so = ((((size_t)jl * SB + s) * WH + h) * WN + i) * WN + 4 * cg;
;                 f32x4 S = qS[q];
;                 const float sa = row16_sum((S.x * nk.x + S.y * nk.y) + (S.z * nk.z + S.w * nk.w));
;                 S.x = fmaf(S.x, w4.x, fmaf(sa, ka.x, vi * k4.x)); S.y = fmaf(S.y, w4.y, fmaf(sa, ka.y, vi * k4.y));
;                 S.z = fmaf(S.z, w4.z, fmaf(sa, ka.z, vi * k4.z)); S.w = fmaf(S.w, w4.w, fmaf(sa, ka.w, vi * k4.w));
;                 const float y = row16_sum((S.x * r4.x + S.y * r4.y) + (S.z * r4.z + S.w * r4.w));
;                 *(f32x4*)(p.out + O_WKVS + so) = S;
;                 if (cg == 0) YW[(size_t)row * D + h * WN + i] = bf_cv(y);
;                 const f32x4 rk4 = *(const f32x4*)(p.in[I_RK] + (size_t)jl * D + ch);
;                 const float bon = row16_sum((r4.x * k4.x * rk4.x + r4.y * k4.y * rk4.y) + (r4.z * k4.z * rk4.z + r4.w * k4.w * rk4.w));
.LBB0_151:
	v_lshlrev_b32_e32 v85, 16, v78
	v_add_f32_e32 v0, v0, v100
	v_add_f32_e32 v26, v26, v85
	v_max_f32_e32 v0, 0x2b8cbccc, v0
	v_mul_f32_e32 v26, 0xbfb8aa3b, v26
	v_rsq_f32_e32 v0, v0
	v_exp_f32_e32 v26, v26
	v_and_b32_e32 v101, 0xffff0000, v78
	v_lshlrev_b32_e32 v102, 16, v79
	v_and_b32_e32 v103, 0xffff0000, v79
	v_lshlrev_b32_e32 v104, 16, v76
	v_and_b32_e32 v105, 0xffff0000, v76
	v_lshlrev_b32_e32 v106, 16, v77
	v_and_b32_e32 v85, 0xffff0000, v77
	v_pk_mul_f32 v[76:77], v[94:95], v[0:1] op_sel_hi:[1,0] neg_lo:[0,1] neg_hi:[0,1]
	v_pk_mul_f32 v[78:79], v[96:97], v[0:1] op_sel_hi:[1,0] neg_lo:[0,1] neg_hi:[0,1]
	v_add_f32_e32 v0, 1.0, v26
	v_rcp_f32_e32 v0, v0
	v_add_f32_e32 v26, v27, v101
	v_mul_f32_e32 v26, 0xbfb8aa3b, v26
	v_exp_f32_e32 v27, v26
	v_mul_f32_e32 v0, 0xbf1b4598, v0
	v_mul_f32_e32 v0, 0x3fb8aa3b, v0
	v_exp_f32_e32 v26, v0
	v_add_f32_e32 v0, 1.0, v27
	v_rcp_f32_e32 v0, v0
	v_add_f32_e32 v27, v28, v102
	v_mul_f32_e32 v27, 0xbfb8aa3b, v27
	v_exp_f32_e32 v28, v27
	v_mul_f32_e32 v0, 0xbf1b4598, v0
	v_mul_f32_e32 v0, 0x3fb8aa3b, v0
	v_exp_f32_e32 v27, v0
	v_add_f32_e32 v0, 1.0, v28
	v_rcp_f32_e32 v0, v0
	v_add_f32_e32 v28, v29, v103
	v_mul_f32_e32 v28, 0xbfb8aa3b, v28
	v_exp_f32_e32 v29, v28
	v_mul_f32_e32 v0, 0xbf1b4598, v0
	v_mul_f32_e32 v0, 0x3fb8aa3b, v0
	v_exp_f32_e32 v28, v0
	v_add_f32_e32 v0, 1.0, v29
	v_rcp_f32_e32 v0, v0
	v_add_f32_e32 v18, v18, v104
	v_mul_f32_e32 v18, 0xbfb8aa3b, v18
	v_exp_f32_e32 v18, v18
	v_mul_f32_e32 v0, 0xbf1b4598, v0
	v_mul_f32_e32 v0, 0x3fb8aa3b, v0
	v_exp_f32_e32 v29, v0
	v_add_f32_e32 v0, 1.0, v18
	v_rcp_f32_e32 v18, v0
	v_add_f32_e32 v0, v19, v105
	v_add_f32_e32 v19, v20, v106
	v_mul_f32_e32 v19, 0xbfb8aa3b, v19
	v_mul_f32_e32 v0, 0xbfb8aa3b, v0
	v_exp_f32_e32 v20, v19
	v_add_f32_e32 v19, v21, v85
	v_exp_f32_e32 v0, v0
	v_mul_f32_e32 v19, 0xbfb8aa3b, v19
	v_exp_f32_e32 v21, v19
	s_and_b32 s57, s27, 15
	v_add_f32_e32 v0, 1.0, v0
	v_rcp_f32_e32 v19, v0
	v_add_f32_e32 v0, 1.0, v20
	v_add_f32_e32 v20, 1.0, v21
	v_rcp_f32_e32 v21, v20
	v_rcp_f32_e32 v20, v0
	v_or_b32_e32 v0, s57, v31
	v_xor_b32_e32 v95, 0x80000000, v19
	v_xor_b32_e32 v94, 0x80000000, v18
	v_xor_b32_e32 v97, 0x80000000, v21
	v_xor_b32_e32 v96, 0x80000000, v20
	v_pk_add_f32 v[20:21], v[20:21], -1.0 op_sel_hi:[1,0]
	v_pk_add_f32 v[18:19], v[18:19], -1.0 op_sel_hi:[1,0]
	v_lshlrev_b32_e32 v0, 2, v0
	s_waitcnt vmcnt(0)
	v_pk_fma_f32 v[22:23], v[22:23], v[18:19], 1.0 op_sel_hi:[1,1,0]
	v_pk_fma_f32 v[18:19], v[24:25], v[20:21], 1.0 op_sel_hi:[1,1,0]
	ds_bpermute_b32 v24, v0, v86
	ds_bpermute_b32 v25, v0, v87
	ds_bpermute_b32 v85, v0, v89
	ds_bpermute_b32 v0, v0, v88
	v_pk_mul_f32 v[20:21], v[22:23], v[90:91]
	v_pk_mul_f32 v[96:97], v[76:77], v[96:97]
	s_waitcnt lgkmcnt(2)
	v_cndmask_b32_e64 v22, v25, v24, s[8:9]
	s_waitcnt lgkmcnt(1)
	v_cndmask_b32_e64 v22, v22, v85, s[6:7]
	s_waitcnt lgkmcnt(0)
	v_cndmask_b32_e64 v0, v22, v0, s[4:5]
	v_pk_mul_f32 v[22:23], v[16:17], v[76:77]
	v_pk_mul_f32 v[24:25], v[14:15], v[78:79]
	v_pk_mul_f32 v[94:95], v[78:79], v[94:95]
	v_pk_mov_b32 v[76:77], v[24:25], v[22:23] op_sel:[1,0]
	v_mov_b32_e32 v25, v23
	v_pk_add_f32 v[22:23], v[76:77], v[24:25]
	v_pk_mul_f32 v[18:19], v[18:19], v[92:93]
	v_add_f32_e32 v22, v22, v23
	v_lshlrev_b32_e32 v82, 16, v80
	v_and_b32_e32 v83, 0xffff0000, v80
	v_add_f32_dpp v22, v22, v22 row_ror:8 row_mask:0xf bank_mask:0xf bound_ctrl:1
	v_lshlrev_b32_e32 v80, 16, v81
	v_and_b32_e32 v81, 0xffff0000, v81
	v_add_f32_dpp v22, v22, v22 row_ror:4 row_mask:0xf bank_mask:0xf bound_ctrl:1
	s_lshl_b64 s[40:41], s[40:41], 4
	s_add_u32 s40, s40, s48
	v_add_f32_dpp v22, v22, v22 row_ror:2 row_mask:0xf bank_mask:0xf bound_ctrl:1
	s_addc_u32 s41, s41, 0
	s_or_b32 s40, s40, s42
	v_add_f32_dpp v24, v22, v22 row_ror:1 row_mask:0xf bank_mask:0xf bound_ctrl:1
	v_pk_mul_f32 v[22:23], v[20:21], v[0:1] op_sel_hi:[1,0]
	s_lshl_b64 s[40:41], s[40:41], 14
	v_pk_fma_f32 v[22:23], v[24:25], v[94:95], v[22:23] op_sel_hi:[0,1,1]
	v_pk_fma_f32 v[22:23], v[14:15], v[26:27], v[22:23]
	v_pk_mul_f32 v[14:15], v[18:19], v[0:1] op_sel_hi:[1,0]
	v_mul_f32_e32 v0, v23, v83
	v_pk_fma_f32 v[14:15], v[24:25], v[96:97], v[14:15] op_sel_hi:[0,1,1]
	v_pk_fma_f32 v[24:25], v[16:17], v[28:29], v[14:15]
	v_fmac_f32_e32 v0, v22, v82
	v_mul_f32_e32 v14, v25, v81
	v_fmac_f32_e32 v14, v24, v80
	v_add_f32_e32 v0, v0, v14
	v_readlane_b32 s58, v252, 52
	v_lshl_or_b32 v84, s57, 2, v151
	v_add_f32_dpp v0, v0, v0 row_ror:8 row_mask:0xf bank_mask:0xf bound_ctrl:1
	s_add_u32 s40, s58, s40
	v_readlane_b32 s58, v252, 53
	v_add_f32_dpp v0, v0, v0 row_ror:4 row_mask:0xf bank_mask:0xf bound_ctrl:1
	s_addc_u32 s41, s58, s41
	v_mov_b32_e32 v15, v1
	v_add_f32_dpp v14, v0, v0 row_ror:2 row_mask:0xf bank_mask:0xf bound_ctrl:1
	v_lshlrev_b32_e32 v0, 8, v84
	v_lshl_add_u64 v[16:17], s[40:41], 0, v[0:1]
	v_lshlrev_b32_e32 v0, 2, v30
	v_mov_b32_dpp v15, v14 row_ror:1 row_mask:0xf bank_mask:0xf
	v_lshl_add_u64 v[16:17], v[16:17], 0, v[0:1]
	global_store_dwordx4 v[16:17], v[22:25], off nt
	s_and_saveexec_b64 s[40:41], s[10:11]
	s_cbranch_execz .LBB0_153
	s_lshl_b64 s[58:59], s[36:37], 1
	v_readlane_b32 s60, v254, 56
	v_readlane_b32 s61, v254, 57
	s_add_u32 s58, s60, s58
	s_addc_u32 s59, s61, s59
	s_lshl_b32 s43, s43, 1
	v_add_f32_e32 v14, v14, v15
	s_add_u32 s58, s58, s43
	v_cvt_pk_bf16_f32 v14, v14, s0
	s_addc_u32 s59, s59, 0
	v_lshlrev_b32_e32 v15, 1, v84
	global_store_short v15, v14, s[58:59]

; __device__ __forceinline__ f32x4 wk_unit_neg(const f32x4 kraw, const f32x4 kkp) {
;     const f32x4 kk = kraw * kkp;
;     const float ss = row16_sum((kk.x * kk.x + kk.y * kk.y) + (kk.z * kk.z + kk.w * kk.w));
;     return kk * (-rsqrtf(fmaxf(ss, 1e-12f)));
; }
; __device__ __forceinline__ void ph_wkv2(const Params& p, int jl, int lane, int wave) {
;     ...
;                 const int rg = it & 15, h = (it >> 4) & 15, s = it >> 8, row = MP + s, i = 4 * rg + ri;
;                 const int ch = h * WN + 4 * cg;
;                 WkPar P; P.w0 = *(const f32x4*)(p.in[I_W0] + (size_t)jl * D + ch); P.a0 = *(const f32x4*)(p.in[I_A0] + (size_t)jl * D + ch); P.kkp = *(const f32x4*)(p.in[I_KK] + (size_t)jl * D + ch);
;                 P.kap = *(const f32x4*)(p.in[I_KA] + (size_t)jl * D + ch); P.v0 = *(const f32x4*)(p.in[I_V0] + ch);
;                 const size_t vo = (size_t)row * D + ch;
;     ...
;                 const f32x4 kraw = W2_UP4(qk[q]), vraw = W2_UP4(qv[q]), r4 = W2_UP4(qr[q]), lw2 = W2_UP4(qlw[q]), la2 = W2_UP4(qla[q]), vf = W2_UP4(qvf[q]), lv2 = W2_UP4(qlv[q]);
;     ...
;                 f32x4 w4, ka, k4, vp, nk; wk_prep(P, kraw, vraw, lw2, la2, vf, lv2, vres, w4, ka, k4, vp, nk);
;                 const int srcl = (lane & 48) | rg;
;                 const float v0_ = shfl_l(vp.x, srcl), v1_ = shfl_l(vp.y, srcl), v2_ = shfl_l(vp.z, srcl), v3_ = shfl_l(vp.w, srcl);
;                 const float vi = ri == 0 ? v0_ : (ri == 1 ? v1_ : (ri == 2 ? v2_ : v3_));
;                 const size_t so = ((((size_t)jl * SB + s) * WH + h) * WN + i) * WN + 4 * cg;
;                 f32x4 S = qS[q];
;                 const float sa = row16_sum((S.x * nk.x + S.y * nk.y) + (S.z * nk.z + S.w * nk.w));
;                 S.x = fmaf(S.x, w4.x, fmaf(sa, ka.x, vi * k4.x)); S.y = fmaf(S.y, w4.y, fmaf(sa, ka.y, vi * k4.y));
;                 S.z = fmaf(S.z, w4.z, fmaf(sa, ka.z, vi * k4.z)); S.w = fmaf(S.w, w4.w, fmaf(sa, ka.w, vi * k4.w));
;                 const float y = row16_sum((S.x * r4.x + S.y * r4.y) + (S.z * r4.z + S.w * r4.w));
;                 *(f32x4*)(p.out + O_WKVS + so) = S;
;                 if (cg == 0) YW[(size_t)row * D + h * WN + i] = bf_cv(y);
;                 const f32x4 rk4 = *(const f32x4*)(p.in[I_RK] + (size_t)jl * D + ch);
;                 const float bon = row16_sum((r4.x * k4.x * rk4.x + r4.y * k4.y * rk4.y) + (r4.z * k4.z * rk4.z + r4.w * k4.w * rk4.w));
.LBB0_161:
	v_lshlrev_b32_e32 v71, 16, v64
	v_lshlrev_b32_e32 v87, 16, v62
	v_and_b32_e32 v88, 0xffff0000, v62
	v_lshlrev_b32_e32 v89, 16, v63
	v_add_f32_e32 v22, v22, v71
	v_and_b32_e32 v71, 0xffff0000, v63
	v_add_f32_e32 v18, v18, v87
	v_add_f32_e32 v19, v19, v88
	v_add_f32_e32 v20, v20, v89
	v_add_f32_e32 v21, v21, v71
	v_mul_f32_e32 v18, 0xbfb8aa3b, v18
	v_mul_f32_e32 v19, 0xbfb8aa3b, v19
	v_mul_f32_e32 v20, 0xbfb8aa3b, v20
	v_mul_f32_e32 v21, 0xbfb8aa3b, v21
	v_exp_f32_e32 v18, v18
	v_exp_f32_e32 v19, v19
	v_exp_f32_e32 v20, v20
	v_exp_f32_e32 v21, v21
	v_add_f32_e32 v62, v82, v83
	v_max_f32_e32 v62, 0x2b8cbccc, v62
	v_add_f32_e32 v18, 1.0, v18
	v_add_f32_e32 v19, 1.0, v19
	v_add_f32_e32 v20, 1.0, v20
	v_add_f32_e32 v21, 1.0, v21
	v_rsq_f32_e32 v62, v62
	v_rcp_f32_e32 v18, v18
	v_rcp_f32_e32 v19, v19
	v_rcp_f32_e32 v21, v21
	v_rcp_f32_e32 v20, v20
	s_and_b32 s42, s56, 15
	v_and_b32_e32 v84, 0xffff0000, v64
	v_lshlrev_b32_e32 v85, 16, v65
	v_and_b32_e32 v86, 0xffff0000, v65
	v_pk_mul_f32 v[64:65], v[72:73], v[62:63] op_sel_hi:[1,0] neg_lo:[0,1] neg_hi:[0,1]
	v_pk_mul_f32 v[62:63], v[78:79], v[62:63] op_sel_hi:[1,0] neg_lo:[0,1] neg_hi:[0,1]
	v_xor_b32_e32 v73, 0x80000000, v19
	v_xor_b32_e32 v72, 0x80000000, v18
	v_xor_b32_e32 v79, 0x80000000, v21
	v_xor_b32_e32 v78, 0x80000000, v20
	v_pk_add_f32 v[20:21], v[20:21], -1.0 op_sel_hi:[1,0]
	v_pk_add_f32 v[18:19], v[18:19], -1.0 op_sel_hi:[1,0]
	v_add_f32_e32 v23, v23, v84
	s_waitcnt vmcnt(0)
	v_pk_fma_f32 v[18:19], v[14:15], v[18:19], 1.0 op_sel_hi:[1,1,0]
	v_pk_fma_f32 v[14:15], v[16:17], v[20:21], 1.0 op_sel_hi:[1,1,0]
	v_or_b32_e32 v16, s42, v31
	v_lshlrev_b32_e32 v16, 2, v16
	v_mul_f32_e32 v22, 0xbfb8aa3b, v22
	v_mul_f32_e32 v23, 0xbfb8aa3b, v23
	ds_bpermute_b32 v20, v16, v26
	ds_bpermute_b32 v21, v16, v27
	v_exp_f32_e32 v22, v22
	v_exp_f32_e32 v23, v23
	v_add_f32_e32 v24, v24, v85
	v_add_f32_e32 v25, v25, v86
	ds_bpermute_b32 v71, v16, v29
	v_mul_f32_e32 v24, 0xbfb8aa3b, v24
	v_mul_f32_e32 v25, 0xbfb8aa3b, v25
	ds_bpermute_b32 v82, v16, v28
	v_exp_f32_e32 v24, v24
	v_exp_f32_e32 v25, v25
	v_add_f32_e32 v22, 1.0, v22
	v_add_f32_e32 v23, 1.0, v23
	v_pk_mul_f32 v[16:17], v[18:19], v[76:77]
	s_waitcnt lgkmcnt(2)
	v_cndmask_b32_e64 v18, v21, v20, s[8:9]
	v_rcp_f32_e32 v22, v22
	v_rcp_f32_e32 v23, v23
	s_waitcnt lgkmcnt(1)
	v_cndmask_b32_e64 v18, v18, v71, s[6:7]
	v_add_f32_e32 v24, 1.0, v24
	v_add_f32_e32 v25, 1.0, v25
	v_pk_mul_f32 v[72:73], v[62:63], v[72:73]
	s_waitcnt lgkmcnt(0)
	v_cndmask_b32_e64 v20, v18, v82, s[4:5]
	v_pk_mul_f32 v[18:19], v[12:13], v[64:65]
	v_pk_mul_f32 v[62:63], v[10:11], v[62:63]
	v_rcp_f32_e32 v24, v24
	v_rcp_f32_e32 v25, v25
	v_pk_mul_f32 v[78:79], v[64:65], v[78:79]
	v_pk_mov_b32 v[64:65], v[62:63], v[18:19] op_sel:[1,0]
	v_mov_b32_e32 v63, v19
	v_pk_add_f32 v[18:19], v[64:65], v[62:63]
	v_mul_f32_e32 v22, 0xbf1b4598, v22
	v_mul_f32_e32 v23, 0xbf1b4598, v23
	v_add_f32_e32 v18, v18, v19
	v_mul_f32_e32 v22, 0x3fb8aa3b, v22
	v_mul_f32_e32 v23, 0x3fb8aa3b, v23
	v_add_f32_dpp v18, v18, v18 row_ror:8 row_mask:0xf bank_mask:0xf bound_ctrl:1
	v_exp_f32_e32 v22, v22
	v_exp_f32_e32 v23, v23
	v_mul_f32_e32 v24, 0xbf1b4598, v24
	v_mul_f32_e32 v25, 0xbf1b4598, v25
	v_add_f32_dpp v18, v18, v18 row_ror:4 row_mask:0xf bank_mask:0xf bound_ctrl:1
	v_mul_f32_e32 v24, 0x3fb8aa3b, v24
	v_mul_f32_e32 v25, 0x3fb8aa3b, v25
	v_add_f32_dpp v18, v18, v18 row_ror:2 row_mask:0xf bank_mask:0xf bound_ctrl:1
	v_exp_f32_e32 v24, v24
	v_exp_f32_e32 v25, v25
	v_add_f32_dpp v62, v18, v18 row_ror:1 row_mask:0xf bank_mask:0xf bound_ctrl:1
	v_pk_mul_f32 v[18:19], v[16:17], v[20:21] op_sel_hi:[1,0]
	s_ashr_i32 s38, s56, 8
	v_pk_mul_f32 v[14:15], v[14:15], v[74:75]
	v_pk_fma_f32 v[18:19], v[62:63], v[72:73], v[18:19] op_sel_hi:[0,1,1]
	s_add_i32 s34, s38, 0x4080
	v_pk_fma_f32 v[18:19], v[10:11], v[22:23], v[18:19]
	v_pk_mul_f32 v[10:11], v[14:15], v[20:21] op_sel_hi:[1,0]
	s_ashr_i32 s35, s34, 31
	s_ashr_i32 s39, s38, 31
	v_pk_fma_f32 v[10:11], v[62:63], v[78:79], v[10:11] op_sel_hi:[0,1,1]
	s_lshl_b64 s[36:37], s[34:35], 10
	v_lshlrev_b32_e32 v68, 16, v66
	v_and_b32_e32 v69, 0xffff0000, v66
	v_lshlrev_b32_e32 v66, 16, v67
	v_and_b32_e32 v67, 0xffff0000, v67
	s_lshl_b64 s[38:39], s[38:39], 4
	v_pk_fma_f32 v[20:21], v[12:13], v[24:25], v[10:11]
	s_add_u32 s38, s38, s48
	v_mul_f32_e32 v10, v19, v69
	v_mul_f32_e32 v11, v21, v67
	s_addc_u32 s39, s39, 0
	s_or_b32 s38, s38, s40
	v_fmac_f32_e32 v10, v18, v68
	v_fmac_f32_e32 v11, v20, v66
	v_add_f32_e32 v10, v10, v11
	s_lshl_b64 s[38:39], s[38:39], 14
	v_readlane_b32 s43, v252, 52
	v_lshl_or_b32 v70, s42, 2, v151
	v_add_f32_dpp v10, v10, v10 row_ror:8 row_mask:0xf bank_mask:0xf bound_ctrl:1
	s_add_u32 s38, s43, s38
	v_readlane_b32 s43, v252, 53
	v_add_f32_dpp v10, v10, v10 row_ror:4 row_mask:0xf bank_mask:0xf bound_ctrl:1
	s_addc_u32 s39, s43, s39
	v_lshlrev_b32_e32 v12, 8, v70
	v_mov_b32_e32 v13, v1
	v_add_f32_dpp v10, v10, v10 row_ror:2 row_mask:0xf bank_mask:0xf bound_ctrl:1
	v_mov_b32_e32 v11, v1
	v_lshl_add_u64 v[12:13], s[38:39], 0, v[12:13]
	v_lshl_add_u64 v[12:13], v[12:13], 0, v[0:1]
	v_mov_b32_dpp v11, v10 row_ror:1 row_mask:0xf bank_mask:0xf
	global_store_dwordx4 v[12:13], v[18:21], off nt
	s_and_saveexec_b64 s[38:39], s[10:11]
	s_cbranch_execz .LBB0_163
	s_lshl_b64 s[56:57], s[36:37], 1
	v_readlane_b32 s58, v254, 56
	v_readlane_b32 s59, v254, 57
	s_add_u32 s43, s58, s56
	s_addc_u32 s57, s59, s57
	s_lshl_b32 s41, s41, 1
	v_add_f32_e32 v10, v10, v11
	s_add_u32 s56, s43, s41
	v_cvt_pk_bf16_f32 v10, v10, s0
	s_addc_u32 s57, s57, 0
	v_lshlrev_b32_e32 v11, 1, v70
	global_store_short v11, v10, s[56:57]

; __device__ __forceinline__ f32x4 wk_unit_neg(const f32x4 kraw, const f32x4 kkp) {
;     const f32x4 kk = kraw * kkp;
;     const float ss = row16_sum((kk.x * kk.x + kk.y * kk.y) + (kk.z * kk.z + kk.w * kk.w));
;     return kk * (-rsqrtf(fmaxf(ss, 1e-12f)));
; }
; __device__ __forceinline__ void ph_wkv2(const Params& p, int jl, int lane, int wave) {
;     ...
;                 const int rg = it & 15, h = (it >> 4) & 15, s = it >> 8, row = MP + s, i = 4 * rg + ri;
;                 const int ch = h * WN + 4 * cg;
;                 WkPar P; P.w0 = *(const f32x4*)(p.in[I_W0] + (size_t)jl * D + ch); P.a0 = *(const f32x4*)(p.in[I_A0] + (size_t)jl * D + ch); P.kkp = *(const f32x4*)(p.in[I_KK] + (size_t)jl * D + ch);
;                 P.kap = *(const f32x4*)(p.in[I_KA] + (size_t)jl * D + ch); P.v0 = *(const f32x4*)(p.in[I_V0] + ch);
;                 const size_t vo = (size_t)row * D + ch;
;     ...
;                 const f32x4 kraw = W2_UP4(qk[q]), vraw = W2_UP4(qv[q]), r4 = W2_UP4(qr[q]), lw2 = W2_UP4(qlw[q]), la2 = W2_UP4(qla[q]), vf = W2_UP4(qvf[q]), lv2 = W2_UP4(qlv[q]);
;     ...
;                 f32x4 w4, ka, k4, vp, nk; wk_prep(P, kraw, vraw, lw2, la2, vf, lv2, vres, w4, ka, k4, vp, nk);
;                 const int srcl = (lane & 48) | rg;
;                 const float v0_ = shfl_l(vp.x, srcl), v1_ = shfl_l(vp.y, srcl), v2_ = shfl_l(vp.z, srcl), v3_ = shfl_l(vp.w, srcl);
;                 const float vi = ri == 0 ? v0_ : (ri == 1 ? v1_ : (ri == 2 ? v2_ : v3_));
;                 const size_t so = ((((size_t)jl * SB + s) * WH + h) * WN + i) * WN + 4 * cg;
;                 f32x4 S = qS[q];
;                 const float sa = row16_sum((S.x * nk.x + S.y * nk.y) + (S.z * nk.z + S.w * nk.w));
;                 S.x = fmaf(S.x, w4.x, fmaf(sa, ka.x, vi * k4.x)); S.y = fmaf(S.y, w4.y, fmaf(sa, ka.y, vi * k4.y));
;                 S.z = fmaf(S.z, w4.z, fmaf(sa, ka.z, vi * k4.z)); S.w = fmaf(S.w, w4.w, fmaf(sa, ka.w, vi * k4.w));
;                 const float y = row16_sum((S.x * r4.x + S.y * r4.y) + (S.z * r4.z + S.w * r4.w));
;                 *(f32x4*)(p.out + O_WKVS + so) = S;
;                 if (cg == 0) YW[(size_t)row * D + h * WN + i] = bf_cv(y);
;                 const f32x4 rk4 = *(const f32x4*)(p.in[I_RK] + (size_t)jl * D + ch);
;                 const float bon = row16_sum((r4.x * k4.x * rk4.x + r4.y * k4.y * rk4.y) + (r4.z * k4.z * rk4.z + r4.w * k4.w * rk4.w));
.LBB0_173:
	v_lshlrev_b32_e32 v57, 16, v50
	v_lshlrev_b32_e32 v69, 16, v48
	v_and_b32_e32 v70, 0xffff0000, v48
	v_lshlrev_b32_e32 v71, 16, v49
	v_add_f32_e32 v18, v18, v57
	v_and_b32_e32 v57, 0xffff0000, v49
	v_add_f32_e32 v14, v14, v69
	v_add_f32_e32 v15, v15, v70
	v_add_f32_e32 v16, v16, v71
	v_add_f32_e32 v17, v17, v57
	v_mul_f32_e32 v14, 0xbfb8aa3b, v14
	v_mul_f32_e32 v15, 0xbfb8aa3b, v15
	v_mul_f32_e32 v16, 0xbfb8aa3b, v16
	v_mul_f32_e32 v17, 0xbfb8aa3b, v17
	v_exp_f32_e32 v14, v14
	v_exp_f32_e32 v15, v15
	v_exp_f32_e32 v16, v16
	v_exp_f32_e32 v17, v17
	v_add_f32_e32 v48, v64, v65
	v_max_f32_e32 v48, 0x2b8cbccc, v48
	v_add_f32_e32 v14, 1.0, v14
	v_add_f32_e32 v15, 1.0, v15
	v_add_f32_e32 v16, 1.0, v16
	v_add_f32_e32 v17, 1.0, v17
	v_rsq_f32_e32 v48, v48
	v_rcp_f32_e32 v14, v14
	v_rcp_f32_e32 v15, v15
	v_rcp_f32_e32 v17, v17
	v_rcp_f32_e32 v16, v16
	s_and_b32 s40, s55, 15
	v_and_b32_e32 v66, 0xffff0000, v50
	v_lshlrev_b32_e32 v67, 16, v51
	v_and_b32_e32 v68, 0xffff0000, v51
	v_pk_mul_f32 v[50:51], v[58:59], v[48:49] op_sel_hi:[1,0] neg_lo:[0,1] neg_hi:[0,1]
	v_pk_mul_f32 v[48:49], v[60:61], v[48:49] op_sel_hi:[1,0] neg_lo:[0,1] neg_hi:[0,1]
	v_xor_b32_e32 v59, 0x80000000, v15
	v_xor_b32_e32 v58, 0x80000000, v14
	v_xor_b32_e32 v61, 0x80000000, v17
	v_xor_b32_e32 v60, 0x80000000, v16
	v_pk_add_f32 v[16:17], v[16:17], -1.0 op_sel_hi:[1,0]
	v_pk_add_f32 v[14:15], v[14:15], -1.0 op_sel_hi:[1,0]
	v_add_f32_e32 v19, v19, v66
	s_waitcnt vmcnt(0)
	v_pk_fma_f32 v[14:15], v[10:11], v[14:15], 1.0 op_sel_hi:[1,1,0]
	v_pk_fma_f32 v[10:11], v[12:13], v[16:17], 1.0 op_sel_hi:[1,1,0]
	v_or_b32_e32 v12, s40, v31
	v_lshlrev_b32_e32 v12, 2, v12
	v_mul_f32_e32 v18, 0xbfb8aa3b, v18
	v_mul_f32_e32 v19, 0xbfb8aa3b, v19
	ds_bpermute_b32 v16, v12, v22
	ds_bpermute_b32 v17, v12, v23
	v_exp_f32_e32 v18, v18
	v_exp_f32_e32 v19, v19
	v_add_f32_e32 v20, v20, v67
	v_add_f32_e32 v21, v21, v68
	ds_bpermute_b32 v57, v12, v25
	v_mul_f32_e32 v20, 0xbfb8aa3b, v20
	v_mul_f32_e32 v21, 0xbfb8aa3b, v21
	ds_bpermute_b32 v64, v12, v24
	v_exp_f32_e32 v20, v20
	v_exp_f32_e32 v21, v21
	v_add_f32_e32 v18, 1.0, v18
	v_add_f32_e32 v19, 1.0, v19
	v_pk_mul_f32 v[12:13], v[14:15], v[26:27]
	s_waitcnt lgkmcnt(2)
	v_cndmask_b32_e64 v14, v17, v16, s[8:9]
	v_rcp_f32_e32 v18, v18
	v_rcp_f32_e32 v19, v19
	s_waitcnt lgkmcnt(1)
	v_cndmask_b32_e64 v14, v14, v57, s[6:7]
	v_add_f32_e32 v20, 1.0, v20
	v_add_f32_e32 v21, 1.0, v21
	s_waitcnt lgkmcnt(0)
	v_cndmask_b32_e64 v16, v14, v64, s[4:5]
	v_pk_mul_f32 v[14:15], v[8:9], v[50:51]
	v_pk_mul_f32 v[26:27], v[6:7], v[48:49]
	v_rcp_f32_e32 v20, v20
	v_rcp_f32_e32 v21, v21
	v_pk_mul_f32 v[10:11], v[10:11], v[28:29]
	v_pk_mov_b32 v[28:29], v[26:27], v[14:15] op_sel:[1,0]
	v_mov_b32_e32 v27, v15
	v_pk_add_f32 v[14:15], v[28:29], v[26:27]
	v_mul_f32_e32 v18, 0xbf1b4598, v18
	v_mul_f32_e32 v19, 0xbf1b4598, v19
	v_add_f32_e32 v14, v14, v15
	v_mul_f32_e32 v18, 0x3fb8aa3b, v18
	v_mul_f32_e32 v19, 0x3fb8aa3b, v19
	v_add_f32_dpp v14, v14, v14 row_ror:8 row_mask:0xf bank_mask:0xf bound_ctrl:1
	v_exp_f32_e32 v18, v18
	v_exp_f32_e32 v19, v19
	v_mul_f32_e32 v20, 0xbf1b4598, v20
	v_mul_f32_e32 v21, 0xbf1b4598, v21
	v_add_f32_dpp v14, v14, v14 row_ror:4 row_mask:0xf bank_mask:0xf bound_ctrl:1
	v_mul_f32_e32 v20, 0x3fb8aa3b, v20
	v_mul_f32_e32 v21, 0x3fb8aa3b, v21
	v_add_f32_dpp v14, v14, v14 row_ror:2 row_mask:0xf bank_mask:0xf bound_ctrl:1
	v_exp_f32_e32 v20, v20
	v_exp_f32_e32 v21, v21
	v_pk_mul_f32 v[58:59], v[48:49], v[58:59]
	v_add_f32_dpp v26, v14, v14 row_ror:1 row_mask:0xf bank_mask:0xf bound_ctrl:1
	v_pk_mul_f32 v[14:15], v[12:13], v[16:17] op_sel_hi:[1,0]
	s_ashr_i32 s36, s55, 8
	v_pk_fma_f32 v[14:15], v[26:27], v[58:59], v[14:15] op_sel_hi:[0,1,1]
	s_add_i32 s30, s36, 0x4080
	v_pk_mul_f32 v[60:61], v[50:51], v[60:61]
	v_pk_fma_f32 v[14:15], v[6:7], v[18:19], v[14:15]
	v_pk_mul_f32 v[6:7], v[10:11], v[16:17] op_sel_hi:[1,0]
	s_ashr_i32 s31, s30, 31
	s_ashr_i32 s37, s36, 31
	v_pk_fma_f32 v[6:7], v[26:27], v[60:61], v[6:7] op_sel_hi:[0,1,1]
	s_lshl_b64 s[34:35], s[30:31], 10
	v_lshlrev_b32_e32 v54, 16, v52
	v_and_b32_e32 v55, 0xffff0000, v52
	v_lshlrev_b32_e32 v52, 16, v53
	v_and_b32_e32 v53, 0xffff0000, v53
	s_lshl_b64 s[36:37], s[36:37], 4
	v_pk_fma_f32 v[16:17], v[8:9], v[20:21], v[6:7]
	s_add_u32 s36, s36, s48
	v_mul_f32_e32 v6, v15, v55
	v_mul_f32_e32 v7, v17, v53
	s_addc_u32 s37, s37, 0
	s_or_b32 s36, s36, s38
	v_fmac_f32_e32 v6, v14, v54
	v_fmac_f32_e32 v7, v16, v52
	v_add_f32_e32 v6, v6, v7
	s_lshl_b64 s[36:37], s[36:37], 14
	v_readlane_b32 s41, v252, 52
	v_lshl_or_b32 v56, s40, 2, v151
	v_add_f32_dpp v6, v6, v6 row_ror:8 row_mask:0xf bank_mask:0xf bound_ctrl:1
	s_add_u32 s36, s41, s36
	v_readlane_b32 s41, v252, 53
	v_add_f32_dpp v6, v6, v6 row_ror:4 row_mask:0xf bank_mask:0xf bound_ctrl:1
	s_addc_u32 s37, s41, s37
	v_lshlrev_b32_e32 v8, 8, v56
	v_mov_b32_e32 v9, v1
	v_add_f32_dpp v6, v6, v6 row_ror:2 row_mask:0xf bank_mask:0xf bound_ctrl:1
	v_mov_b32_e32 v7, v1
	v_lshl_add_u64 v[8:9], s[36:37], 0, v[8:9]
	v_lshl_add_u64 v[8:9], v[8:9], 0, v[0:1]
	v_mov_b32_dpp v7, v6 row_ror:1 row_mask:0xf bank_mask:0xf
	global_store_dwordx4 v[8:9], v[14:17], off nt
	s_and_saveexec_b64 s[36:37], s[10:11]
	s_cbranch_execz .LBB0_175
	s_lshl_b64 s[42:43], s[34:35], 1
	v_readlane_b32 s56, v254, 56
	v_readlane_b32 s57, v254, 57
	s_add_u32 s41, s56, s42
	s_addc_u32 s43, s57, s43
	s_lshl_b32 s39, s39, 1
	v_add_f32_e32 v6, v6, v7
	s_add_u32 s42, s41, s39
	v_cvt_pk_bf16_f32 v6, v6, s0
	s_addc_u32 s43, s43, 0
	v_lshlrev_b32_e32 v7, 1, v56
	global_store_short v7, v6, s[42:43]

; __device__ __forceinline__ f32x4 wk_unit_neg(const f32x4 kraw, const f32x4 kkp) {
;     const f32x4 kk = kraw * kkp;
;     const float ss = row16_sum((kk.x * kk.x + kk.y * kk.y) + (kk.z * kk.z + kk.w * kk.w));
;     return kk * (-rsqrtf(fmaxf(ss, 1e-12f)));
; }
; __device__ __forceinline__ void ph_wkv2(const Params& p, int jl, int lane, int wave) {
;     ...
;                 const int rg = it & 15, h = (it >> 4) & 15, s = it >> 8, row = MP + s, i = 4 * rg + ri;
;                 const int ch = h * WN + 4 * cg;
;                 WkPar P; P.w0 = *(const f32x4*)(p.in[I_W0] + (size_t)jl * D + ch); P.a0 = *(const f32x4*)(p.in[I_A0] + (size_t)jl * D + ch); P.kkp = *(const f32x4*)(p.in[I_KK] + (size_t)jl * D + ch);
;                 P.kap = *(const f32x4*)(p.in[I_KA] + (size_t)jl * D + ch); P.v0 = *(const f32x4*)(p.in[I_V0] + ch);
;                 const size_t vo = (size_t)row * D + ch;
;     ...
;                 const f32x4 kraw = W2_UP4(qk[q]), vraw = W2_UP4(qv[q]), r4 = W2_UP4(qr[q]), lw2 = W2_UP4(qlw[q]), la2 = W2_UP4(qla[q]), vf = W2_UP4(qvf[q]), lv2 = W2_UP4(qlv[q]);
;     ...
;                 f32x4 w4, ka, k4, vp, nk; wk_prep(P, kraw, vraw, lw2, la2, vf, lv2, vres, w4, ka, k4, vp, nk);
;                 const int srcl = (lane & 48) | rg;
;                 const float v0_ = shfl_l(vp.x, srcl), v1_ = shfl_l(vp.y, srcl), v2_ = shfl_l(vp.z, srcl), v3_ = shfl_l(vp.w, srcl);
;                 const float vi = ri == 0 ? v0_ : (ri == 1 ? v1_ : (ri == 2 ? v2_ : v3_));
;                 const size_t so = ((((size_t)jl * SB + s) * WH + h) * WN + i) * WN + 4 * cg;
;                 f32x4 S = qS[q];
;                 const float sa = row16_sum((S.x * nk.x + S.y * nk.y) + (S.z * nk.z + S.w * nk.w));
;                 S.x = fmaf(S.x, w4.x, fmaf(sa, ka.x, vi * k4.x)); S.y = fmaf(S.y, w4.y, fmaf(sa, ka.y, vi * k4.y));
;                 S.z = fmaf(S.z, w4.z, fmaf(sa, ka.z, vi * k4.z)); S.w = fmaf(S.w, w4.w, fmaf(sa, ka.w, vi * k4.w));
;                 const float y = row16_sum((S.x * r4.x + S.y * r4.y) + (S.z * r4.z + S.w * r4.w));
;                 *(f32x4*)(p.out + O_WKVS + so) = S;
;                 if (cg == 0) YW[(size_t)row * D + h * WN + i] = bf_cv(y);
;                 const f32x4 rk4 = *(const f32x4*)(p.in[I_RK] + (size_t)jl * D + ch);
;                 const float bon = row16_sum((r4.x * k4.x * rk4.x + r4.y * k4.y * rk4.y) + (r4.z * k4.z * rk4.z + r4.w * k4.w * rk4.w));
.LBB0_183:
	v_lshlrev_b32_e32 v47, 16, v34
	v_and_b32_e32 v50, 0xffff0000, v34
	v_lshlrev_b32_e32 v51, 16, v35
	v_and_b32_e32 v35, 0xffff0000, v35
	v_add_f32_e32 v10, v10, v47
	v_add_f32_e32 v11, v11, v50
	v_add_f32_e32 v12, v12, v51
	v_add_f32_e32 v13, v13, v35
	v_mul_f32_e32 v10, 0xbfb8aa3b, v10
	v_mul_f32_e32 v11, 0xbfb8aa3b, v11
	v_mul_f32_e32 v12, 0xbfb8aa3b, v12
	v_mul_f32_e32 v13, 0xbfb8aa3b, v13
	v_exp_f32_e32 v10, v10
	v_exp_f32_e32 v11, v11
	v_exp_f32_e32 v12, v12
	v_exp_f32_e32 v13, v13
	v_add_f32_e32 v34, v44, v45
	v_max_f32_e32 v34, 0x2b8cbccc, v34
	v_add_f32_e32 v10, 1.0, v10
	v_add_f32_e32 v11, 1.0, v11
	v_add_f32_e32 v12, 1.0, v12
	v_add_f32_e32 v13, 1.0, v13
	v_rsq_f32_e32 v34, v34
	v_rcp_f32_e32 v10, v10
	v_rcp_f32_e32 v11, v11
	v_rcp_f32_e32 v13, v13
	v_rcp_f32_e32 v12, v12
	v_lshlrev_b32_e32 v43, 16, v36
	v_and_b32_e32 v36, 0xffff0000, v36
	v_lshlrev_b32_e32 v46, 16, v37
	v_and_b32_e32 v37, 0xffff0000, v37
	s_and_b32 s38, s54, 15
	v_pk_mul_f32 v[26:27], v[26:27], v[34:35] op_sel_hi:[1,0] neg_lo:[0,1] neg_hi:[0,1]
	v_pk_mul_f32 v[28:29], v[28:29], v[34:35] op_sel_hi:[1,0] neg_lo:[0,1] neg_hi:[0,1]
	v_add_f32_e32 v15, v15, v36
	v_add_f32_e32 v17, v17, v37
	v_xor_b32_e32 v35, 0x80000000, v11
	v_xor_b32_e32 v34, 0x80000000, v10
	v_xor_b32_e32 v37, 0x80000000, v13
	v_xor_b32_e32 v36, 0x80000000, v12
	v_pk_add_f32 v[12:13], v[12:13], -1.0 op_sel_hi:[1,0]
	v_pk_add_f32 v[10:11], v[10:11], -1.0 op_sel_hi:[1,0]
	v_add_f32_e32 v14, v14, v43
	s_waitcnt vmcnt(0)
	v_pk_fma_f32 v[10:11], v[6:7], v[10:11], 1.0 op_sel_hi:[1,1,0]
	v_pk_fma_f32 v[6:7], v[8:9], v[12:13], 1.0 op_sel_hi:[1,1,0]
	v_or_b32_e32 v8, s38, v31
	v_lshlrev_b32_e32 v8, 2, v8
	v_mul_f32_e32 v14, 0xbfb8aa3b, v14
	v_mul_f32_e32 v15, 0xbfb8aa3b, v15
	ds_bpermute_b32 v12, v8, v18
	ds_bpermute_b32 v13, v8, v19
	v_exp_f32_e32 v14, v14
	v_exp_f32_e32 v15, v15
	v_add_f32_e32 v16, v16, v46
	ds_bpermute_b32 v43, v8, v21
	v_mul_f32_e32 v16, 0xbfb8aa3b, v16
	v_mul_f32_e32 v17, 0xbfb8aa3b, v17
	ds_bpermute_b32 v44, v8, v20
	v_exp_f32_e32 v16, v16
	v_exp_f32_e32 v17, v17
	v_add_f32_e32 v14, 1.0, v14
	v_add_f32_e32 v15, 1.0, v15
	v_pk_mul_f32 v[8:9], v[10:11], v[22:23]
	s_waitcnt lgkmcnt(2)
	v_cndmask_b32_e64 v10, v13, v12, s[8:9]
	v_rcp_f32_e32 v14, v14
	v_rcp_f32_e32 v15, v15
	s_waitcnt lgkmcnt(1)
	v_cndmask_b32_e64 v10, v10, v43, s[6:7]
	v_add_f32_e32 v16, 1.0, v16
	v_add_f32_e32 v17, 1.0, v17
	s_waitcnt lgkmcnt(0)
	v_cndmask_b32_e64 v12, v10, v44, s[4:5]
	v_pk_mul_f32 v[10:11], v[4:5], v[26:27]
	v_pk_mul_f32 v[22:23], v[2:3], v[28:29]
	v_rcp_f32_e32 v16, v16
	v_rcp_f32_e32 v17, v17
	v_pk_mul_f32 v[6:7], v[6:7], v[24:25]
	v_pk_mov_b32 v[24:25], v[22:23], v[10:11] op_sel:[1,0]
	v_mov_b32_e32 v23, v11
	v_pk_add_f32 v[10:11], v[24:25], v[22:23]
	v_mul_f32_e32 v14, 0xbf1b4598, v14
	v_mul_f32_e32 v15, 0xbf1b4598, v15
	v_add_f32_e32 v10, v10, v11
	v_mul_f32_e32 v14, 0x3fb8aa3b, v14
	v_mul_f32_e32 v15, 0x3fb8aa3b, v15
	v_add_f32_dpp v10, v10, v10 row_ror:8 row_mask:0xf bank_mask:0xf bound_ctrl:1
	v_exp_f32_e32 v14, v14
	v_exp_f32_e32 v15, v15
	v_mul_f32_e32 v16, 0xbf1b4598, v16
	v_mul_f32_e32 v17, 0xbf1b4598, v17
	v_add_f32_dpp v10, v10, v10 row_ror:4 row_mask:0xf bank_mask:0xf bound_ctrl:1
	v_mul_f32_e32 v16, 0x3fb8aa3b, v16
	v_mul_f32_e32 v17, 0x3fb8aa3b, v17
	v_add_f32_dpp v10, v10, v10 row_ror:2 row_mask:0xf bank_mask:0xf bound_ctrl:1
	v_exp_f32_e32 v16, v16
	v_exp_f32_e32 v17, v17
	v_pk_mul_f32 v[34:35], v[28:29], v[34:35]
	v_add_f32_dpp v22, v10, v10 row_ror:1 row_mask:0xf bank_mask:0xf bound_ctrl:1
	v_pk_mul_f32 v[10:11], v[8:9], v[12:13] op_sel_hi:[1,0]
	s_ashr_i32 s34, s54, 8
	v_pk_fma_f32 v[10:11], v[22:23], v[34:35], v[10:11] op_sel_hi:[0,1,1]
	s_add_i32 s28, s34, 0x4080
	v_pk_mul_f32 v[36:37], v[26:27], v[36:37]
	v_pk_fma_f32 v[10:11], v[2:3], v[14:15], v[10:11]
	v_pk_mul_f32 v[2:3], v[6:7], v[12:13] op_sel_hi:[1,0]
	s_ashr_i32 s29, s28, 31
	s_ashr_i32 s35, s34, 31
	v_pk_fma_f32 v[2:3], v[22:23], v[36:37], v[2:3] op_sel_hi:[0,1,1]
	s_lshl_b64 s[30:31], s[28:29], 10
	v_lshlrev_b32_e32 v40, 16, v38
	v_and_b32_e32 v41, 0xffff0000, v38
	v_lshlrev_b32_e32 v38, 16, v39
	v_and_b32_e32 v39, 0xffff0000, v39
	s_lshl_b64 s[34:35], s[34:35], 4
	v_pk_fma_f32 v[12:13], v[4:5], v[16:17], v[2:3]
	s_add_u32 s34, s34, s48
	v_mul_f32_e32 v2, v11, v41
	v_mul_f32_e32 v3, v13, v39
	s_addc_u32 s35, s35, 0
	s_or_b32 s34, s34, s36
	v_fmac_f32_e32 v2, v10, v40
	v_fmac_f32_e32 v3, v12, v38
	v_add_f32_e32 v2, v2, v3
	s_lshl_b64 s[34:35], s[34:35], 14
	v_readlane_b32 s39, v252, 52
	v_lshl_or_b32 v42, s38, 2, v151
	v_add_f32_dpp v2, v2, v2 row_ror:8 row_mask:0xf bank_mask:0xf bound_ctrl:1
	s_add_u32 s34, s39, s34
	v_readlane_b32 s39, v252, 53
	v_add_f32_dpp v2, v2, v2 row_ror:4 row_mask:0xf bank_mask:0xf bound_ctrl:1
	s_addc_u32 s35, s39, s35
	v_lshlrev_b32_e32 v4, 8, v42
	v_mov_b32_e32 v5, v1
	v_add_f32_dpp v2, v2, v2 row_ror:2 row_mask:0xf bank_mask:0xf bound_ctrl:1
	v_mov_b32_e32 v3, v1
	v_lshl_add_u64 v[4:5], s[34:35], 0, v[4:5]
	v_lshl_add_u64 v[4:5], v[4:5], 0, v[0:1]
	v_mov_b32_dpp v3, v2 row_ror:1 row_mask:0xf bank_mask:0xf
	global_store_dwordx4 v[4:5], v[10:13], off nt
	s_and_saveexec_b64 s[34:35], s[10:11]
	s_cbranch_execz .LBB0_185
	s_lshl_b64 s[40:41], s[30:31], 1
	v_readlane_b32 s42, v254, 56
	v_readlane_b32 s43, v254, 57
	s_add_u32 s39, s42, s40
	s_addc_u32 s41, s43, s41
	s_lshl_b32 s37, s37, 1
	v_add_f32_e32 v0, v2, v3
	s_add_u32 s40, s39, s37
	v_cvt_pk_bf16_f32 v0, v0, s0
	s_addc_u32 s41, s41, 0
	v_lshlrev_b32_e32 v2, 1, v42
	global_store_short v2, v0, s[40:41]
